# last device-wide barrier (down-projection GEMM -> final norm) replaced by a rendezvous of the four workgroups that own one 256-row block; final-norm rows remapped to those workgroups
# baseline (speedup 1.0000x reference)
; __global__ void __launch_bounds__(NT) mega(Args a) {
;     ...
;     if (blockIdx.x == 0) { unsigned* bw = (unsigned*)(a.ws + WS_BAR); for (int i = threadIdx.x; i < XCD_BAR_WORDS; i += NT) bw[i] = 0u; }
.LBB0_9:
	s_or_b64 exec, exec, s[10:11]
	v_lshlrev_b32_e32 v8, 2, v152
	v_add_u32_e32 v8, 0x3600, v8
	global_store_dword v8, v5, s[8:9]

; __device__ __forceinline__ unsigned xb_ld(unsigned* p)              { return __hip_atomic_load(p, __ATOMIC_RELAXED, __HIP_MEMORY_SCOPE_AGENT); }
; __device__ __forceinline__ unsigned xb_add(unsigned* p, unsigned v) { return __hip_atomic_fetch_add(p, v, __ATOMIC_RELAXED, __HIP_MEMORY_SCOPE_AGENT); }
; #define XB_SPIN(cond, bar) do { unsigned _sp = 0; while (cond) { __builtin_amdgcn_s_sleep(1); \
;     if ((++_sp & 255u) == 0u) { if (xb_ld(&(bar)[XB_TMO])) break; if (_sp > XB_SPIN_CAP) { atomicAdd(&(bar)[XB_TMO], 1u); break; } } } } while (0)
; __device__ __forceinline__ void xcd_barrier(const XcdBarrier& b) {
;     asm volatile("s_waitcnt vmcnt(0)" ::: "memory");
;     __syncthreads();
;     if (threadIdx.x == 0) {
;         unsigned* bar = b.bar;
;         __builtin_amdgcn_s_waitcnt(0);
;         unsigned nloc = b.st[0], nx = b.st[1];
;         if (nloc == 0u) { xcd_barrier_complete(bar, b.x, nloc, nx); b.st[0] = nloc; b.st[1] = nx; }
;         const unsigned old = xb_add(&bar[XB_XSUB(b.x)], 1u);
;         const unsigned gen = old / nloc;
;         if (old + 1u == (gen + 1u) * nloc) {
;             __builtin_amdgcn_fence(__ATOMIC_RELEASE, "agent");
;             asm volatile("s_waitcnt vmcnt(0)" ::: "memory");
;             const unsigned og = xb_add(&bar[XB_TOP], 1u);
;             const unsigned tg = og / nx;
;             if (og + 1u == (tg + 1u) * nx) xb_add(&bar[XB_TOPGEN], 1u);
;             else XB_SPIN(xb_ld(&bar[XB_TOPGEN]) == tg, bar);
;             __builtin_amdgcn_fence(__ATOMIC_ACQUIRE, "agent");
;             xb_add(&bar[XB_XGEN(b.x)], 1u);
;             asm volatile("s_waitcnt vmcnt(0)" ::: "memory");
;         } else {
;             XB_SPIN(xb_ld(&bar[XB_XGEN(b.x)]) == gen, bar);
;             __builtin_amdgcn_fence(__ATOMIC_ACQUIRE, "agent");
;             asm volatile("s_waitcnt vmcnt(0)" ::: "memory");
;         }
;     }
;     __syncthreads();
; }
.LBB0_936:
	s_waitcnt vmcnt(0)
	s_waitcnt lgkmcnt(0)
	s_barrier
	s_mov_b64 s[0:1], exec
	v_readlane_b32 s2, v253, 37
	v_readlane_b32 s3, v253, 38
	s_and_b64 s[2:3], s[0:1], s[2:3]
	s_mov_b64 exec, s[2:3]
	s_cbranch_execz .LBB0_988
	s_and_b32 s5, s82, 7
	s_lshl_b32 s5, s5, 4
	s_bfe_u32 s6, s82, 0x30003
	s_add_u32 s5, s5, s6
	s_lshl_b32 s5, s5, 2
	s_add_u32 s2, s16, 0x1e03600
	s_addc_u32 s3, s17, 0
	v_mov_b32_e32 v0, s5
	v_mov_b32_e32 v1, 1
	global_atomic_add v0, v1, s[2:3]
	global_atomic_add v0, v1, s[2:3] offset:32
	s_mov_b32 s5, 0
.Lg9_spin:
	global_load_dword v2, v0, s[2:3] sc1
	global_load_dword v3, v0, s[2:3] offset:32 sc1
	s_waitcnt vmcnt(0)
	v_min_u32_e32 v2, v2, v3
	s_nop 1
	v_readfirstlane_b32 s6, v2
	s_cmp_ge_u32 s6, 4
	s_cbranch_scc1 .Lg9_done
	s_sleep 1
	s_add_u32 s5, s5, 1
	s_cmp_lt_u32 s5, 0x1000
	s_cbranch_scc1 .Lg9_spin
.Lg9_done:
	buffer_inv sc1
	s_waitcnt vmcnt(0)
	s_branch .LBB0_988
	s_add_i32 s2, 0, 0x20000
	s_waitcnt vmcnt(8)
	v_mov_b32_e32 v0, s2
	s_waitcnt vmcnt(0) expcnt(0) lgkmcnt(0)
	ds_read_b32 v2, v0
	s_add_i32 s2, 0, 0x20004
	v_mov_b32_e32 v0, s2
	ds_read_b32 v0, v0
	s_waitcnt lgkmcnt(1)
	v_cmp_ne_u32_e32 vcc, 0, v2
	s_cbranch_vccnz .LBB0_952
	v_readlane_b32 s2, v253, 0
	s_mul_i32 s33, s81, s2
	s_add_u32 s2, s16, 0x1e00200
	s_addc_u32 s3, s17, 0
	s_add_u32 s4, s16, 0x1e00400
	s_addc_u32 s5, s17, 0
	s_add_u32 s6, s16, 0x1e00500
	s_addc_u32 s7, s17, 0
	s_add_u32 s8, s16, 0x1e00600
	s_addc_u32 s9, s17, 0
	s_add_u32 s10, s16, 0x1e00700
	s_addc_u32 s11, s17, 0
	s_add_u32 s12, s16, 0x1e00800
	s_addc_u32 s13, s17, 0
	s_add_u32 s14, s16, 0x1e00900
	s_addc_u32 s15, s17, 0
	s_add_u32 s18, s16, 0x1e00a00
	s_addc_u32 s19, s17, 0
	s_add_u32 s22, s16, 0x1e00b00
	s_addc_u32 s23, s17, 0
	s_add_u32 s24, s16, 0x1e00c00
	s_addc_u32 s25, s17, 0
	s_add_u32 s26, s16, 0x1e00d00
	s_addc_u32 s27, s17, 0
	s_add_u32 s28, s16, 0x1e00e00
	s_addc_u32 s29, s17, 0
	s_add_u32 s30, s16, 0x1e00f00
	s_addc_u32 s31, s17, 0
	s_add_u32 s34, s16, 0x1e01000
	s_addc_u32 s35, s17, 0
	s_add_u32 s36, s16, 0x1e01100
	s_addc_u32 s37, s17, 0
	s_add_u32 s38, s16, 0x1e01200
	s_addc_u32 s39, s17, 0
	s_add_u32 s40, s16, 0x1e01300
	s_mul_i32 s33, s33, s80
	s_addc_u32 s41, s17, 0
	s_mov_b32 s48, 1
	v_mov_b32_e32 v16, 0
	s_branch .LBB0_940

; __device__ __forceinline__ void unpack8(const u32x4 w, float (&f)[8]) { f[0] = bf_lo(w.x); f[1] = bf_hi(w.x); f[2] = bf_lo(w.y); f[3] = bf_hi(w.y); f[4] = bf_lo(w.z); f[5] = bf_hi(w.z); f[6] = bf_lo(w.w); f[7] = bf_hi(w.w); }
; __device__ __forceinline__ void phase_final(const Args& a) {
;     const int tid = threadIdx.x, lane = tid & 63, wave = tid >> 6; const float* fw = a.in[16];
;     const bf16_t* yb = (const bf16_t*)(a.ws + WS_YB); const float* ss3 = (const float*)(a.ws + WS_SS3);
;     f32x4 nwv[4];
; #pragma unroll
;     for (int j = 0; j < 2; ++j) { nwv[2 * j] = *(const f32x4*)(fw + 512 * j + 8 * lane); nwv[2 * j + 1] = *(const f32x4*)(fw + 512 * j + 8 * lane + 4); }
;     for (int row = blockIdx.x * 8 + wave; row < M; row += gridDim.x * 8) {
;         const u32x4 y0 = *(const u32x4*)(yb + (size_t)row * 1024 + 8 * lane), y1 = *(const u32x4*)(yb + (size_t)row * 1024 + 512 + 8 * lane);
;         const f32x4 s0 = *(const f32x4*)(ss3 + (size_t)row * 16), s1 = *(const f32x4*)(ss3 + (size_t)row * 16 + 4), s2 = *(const f32x4*)(ss3 + (size_t)row * 16 + 8), s3 = *(const f32x4*)(ss3 + (size_t)row * 16 + 12);
;         const float ss = ((s0[0] + s0[1]) + (s0[2] + s0[3])) + ((s1[0] + s1[1]) + (s1[2] + s1[3])) + ((s2[0] + s2[1]) + (s2[2] + s2[3])) + ((s3[0] + s3[1]) + (s3[2] + s3[3]));
;         const float rstd = rsqrtf(ss * (1.0f / 1024.0f) + EPS);
;         float f0[8], f1[8]; unpack8(y0, f0); unpack8(y1, f1);
;         float* op = a.out + (size_t)row * 1024 + 8 * lane;
;         *(f32x4*)op = (f32x4){f0[0], f0[1], f0[2], f0[3]} * rstd * nwv[0]; *(f32x4*)(op + 4) = (f32x4){f0[4], f0[5], f0[6], f0[7]} * rstd * nwv[1];
;         *(f32x4*)(op + 512) = (f32x4){f1[0], f1[1], f1[2], f1[3]} * rstd * nwv[2]; *(f32x4*)(op + 516) = (f32x4){f1[4], f1[5], f1[6], f1[7]} * rstd * nwv[3];
;     }
.LBB0_988:
	s_or_b64 exec, exec, s[0:1]
	v_readlane_b32 s0, v253, 17
	s_bitcmp0_b32 s0, 10
	s_waitcnt lgkmcnt(0)
	s_barrier
	s_cbranch_scc1 .LBB0_992
	s_waitcnt vmcnt(4)
	s_and_b32 s5, s82, 7
	s_lshl_b32 s5, s5, 4
	s_bfe_u32 s6, s82, 0x30003
	s_add_u32 s5, s5, s6
	s_lshl_b32 s5, s5, 8
	s_lshr_b32 s6, s82, 6
	s_lshl_b32 s6, s6, 6
	s_add_u32 s5, s5, s6
	v_lshl_add_u32 v16, v153, 3, s5
	s_mov_b32 s0, 0x8000
	v_cmp_gt_i32_e32 vcc, s0, v16
	s_and_saveexec_b64 s[0:1], vcc
	s_cbranch_execz .LBB0_992
	v_lshlrev_b32_e32 v0, 3, v152
	v_and_b32_e32 v17, 0x1f8, v0
	s_waitcnt vmcnt(3)
	v_lshlrev_b32_e32 v20, 2, v17
	global_load_dwordx4 v[0:3], v20, s[76:77] offset:16
	global_load_dwordx4 v[4:7], v20, s[76:77]
	global_load_dwordx4 v[8:11], v20, s[76:77] offset:2064
	global_load_dwordx4 v[12:15], v20, s[76:77] offset:2048
	s_waitcnt vmcnt(6)
	v_mov_b32_e32 v21, 0
	v_lshl_add_u64 v[18:19], s[78:79], 0, v[20:21]
	v_lshlrev_b32_e32 v20, 1, v17
	v_lshl_add_u64 v[20:21], s[16:17], 0, v[20:21]
	s_mov_b64 s[0:1], 0xc000000
	s_mov_b32 s2, 1
	s_mov_b32 s5, 0
	v_lshl_add_u64 v[20:21], v[20:21], 0, s[0:1]
	s_mov_b64 s[0:1], 0
	v_mov_b32_e32 v22, 0x358637bd
	s_mov_b32 s3, 0x800000
	s_movk_i32 s4, 0x7fff
.LBB0_991:
	v_ashrrev_i32_e32 v17, 31, v16
	s_waitcnt vmcnt(5)
	v_lshlrev_b64 v[24:25], 6, v[16:17]
	v_lshl_add_u64 v[40:41], s[20:21], 0, v[24:25]
	global_load_dwordx4 v[24:27], v[40:41], off
	global_load_dwordx4 v[28:31], v[40:41], off offset:16
	global_load_dwordx4 v[32:35], v[40:41], off offset:32
	global_load_dwordx4 v[36:39], v[40:41], off offset:48
	v_lshlrev_b64 v[40:41], 11, v[16:17]
	v_lshl_add_u64 v[48:49], v[20:21], 0, v[40:41]
	global_load_dwordx4 v[40:43], v[48:49], off
	global_load_dwordx4 v[44:47], v[48:49], off offset:1024
	v_lshlrev_b64 v[48:49], 12, v[16:17]
	v_add_u32_e32 v16, s2, v16
	s_add_u32 s5, s5, 1
	s_cmp_eq_u32 s5, 8
	s_cselect_b32 s6, 0x7f8, 0
	v_add_u32_e32 v16, s6, v16
	s_cmp_ge_u32 s5, 16
	s_cselect_b64 vcc, -1, 0
	s_or_b64 s[0:1], vcc, s[0:1]
	v_lshl_add_u64 v[48:49], v[18:19], 0, v[48:49]
	s_waitcnt vmcnt(5)
	v_mov_b32_e32 v50, v25
	v_mov_b32_e32 v51, v26
	v_mov_b32_e32 v25, v27
	s_waitcnt vmcnt(4)
	v_mov_b32_e32 v26, v29
	v_mov_b32_e32 v27, v30
	v_mov_b32_e32 v29, v31
	v_pk_add_f32 v[24:25], v[50:51], v[24:25]
	v_pk_add_f32 v[26:27], v[26:27], v[28:29]
	v_pk_add_f32 v[24:25], v[24:25], v[24:25] op_sel:[0,1] op_sel_hi:[1,0]
	v_pk_add_f32 v[26:27], v[26:27], v[26:27] op_sel:[0,1] op_sel_hi:[1,0]
	s_waitcnt vmcnt(3)
	v_add_f32_e32 v30, v32, v33
	v_add_f32_e32 v32, v34, v35
	s_waitcnt vmcnt(2)
	v_mov_b32_e32 v31, v38
	v_mov_b32_e32 v33, v39
	v_mov_b32_e32 v25, v36
	v_mov_b32_e32 v27, v37
	v_pk_add_f32 v[28:29], v[30:31], v[32:33]
	v_pk_add_f32 v[24:25], v[24:25], v[26:27]
	s_waitcnt vmcnt(1)
	v_lshlrev_b32_e32 v34, 16, v40
	v_pk_add_f32 v[24:25], v[24:25], v[28:29]
	v_and_b32_e32 v35, 0xffff0000, v40
	v_add_f32_e32 v17, v24, v25
	v_fmamk_f32 v17, v17, 0x3a800000, v22
	v_mul_f32_e32 v23, 0x4b800000, v17
	v_cmp_gt_f32_e32 vcc, s3, v17
	v_lshlrev_b32_e32 v38, 16, v41
	v_and_b32_e32 v39, 0xffff0000, v41
	v_cndmask_b32_e32 v17, v17, v23, vcc
	v_rsq_f32_e32 v17, v17
	v_lshlrev_b32_e32 v40, 16, v42
	v_and_b32_e32 v41, 0xffff0000, v42
	v_lshlrev_b32_e32 v42, 16, v43
	v_mul_f32_e32 v23, 0x45800000, v17
	v_cndmask_b32_e32 v26, v17, v23, vcc
	v_and_b32_e32 v43, 0xffff0000, v43
	s_waitcnt vmcnt(0)
	v_lshlrev_b32_e32 v52, 16, v44
	v_and_b32_e32 v53, 0xffff0000, v44
	v_lshlrev_b32_e32 v44, 16, v45
	v_and_b32_e32 v45, 0xffff0000, v45
	v_lshlrev_b32_e32 v54, 16, v46
	v_and_b32_e32 v55, 0xffff0000, v46
	v_lshlrev_b32_e32 v24, 16, v47
	v_and_b32_e32 v25, 0xffff0000, v47
	v_pk_mul_f32 v[28:29], v[26:27], v[34:35] op_sel_hi:[0,1]
	v_pk_mul_f32 v[30:31], v[26:27], v[38:39] op_sel_hi:[0,1]
	v_pk_mul_f32 v[32:33], v[26:27], v[40:41] op_sel_hi:[0,1]
	v_pk_mul_f32 v[34:35], v[26:27], v[42:43] op_sel_hi:[0,1]
	v_pk_mul_f32 v[36:37], v[26:27], v[52:53] op_sel_hi:[0,1]
	v_pk_mul_f32 v[38:39], v[26:27], v[44:45] op_sel_hi:[0,1]
	v_pk_mul_f32 v[40:41], v[26:27], v[54:55] op_sel_hi:[0,1]
	v_pk_mul_f32 v[42:43], v[26:27], v[24:25] op_sel_hi:[0,1]
	v_pk_mul_f32 v[26:27], v[6:7], v[30:31]
	v_pk_mul_f32 v[24:25], v[4:5], v[28:29]
	v_pk_mul_f32 v[30:31], v[2:3], v[34:35]
	v_pk_mul_f32 v[28:29], v[0:1], v[32:33]
	v_pk_mul_f32 v[34:35], v[14:15], v[38:39]
	v_pk_mul_f32 v[32:33], v[12:13], v[36:37]
	v_pk_mul_f32 v[38:39], v[10:11], v[42:43]
	v_pk_mul_f32 v[36:37], v[8:9], v[40:41]
	global_store_dwordx4 v[48:49], v[24:27], off
	global_store_dwordx4 v[48:49], v[28:31], off offset:16
	global_store_dwordx4 v[48:49], v[32:35], off offset:2048
	global_store_dwordx4 v[48:49], v[36:39], off offset:2064
	s_andn2_b64 exec, exec, s[0:1]
	s_cbranch_execnz .LBB0_991
